# grid barrier poll without the sleep between polls (s_sleep 0)
# speedup vs baseline: 1.0038x; 1.0038x over previous
; __device__ __forceinline__ unsigned xb_ld(unsigned* p)              { return __hip_atomic_load(p, __ATOMIC_RELAXED, __HIP_MEMORY_SCOPE_AGENT); }
; #define XB_SPIN(cond, bar) do { unsigned _sp = 0; while (cond) { __builtin_amdgcn_s_sleep(1); \
;     if ((++_sp & 255u) == 0u) { if (xb_ld(&(bar)[XB_TMO])) break; if (_sp > XB_SPIN_CAP) { atomicAdd(&(bar)[XB_TMO], 1u); break; } } } } while (0)
; __device__ __forceinline__ void xcd_barrier(const XcdBarrier& b, const bool is_t0) {
;     ...
;             XB_SPIN(xb_ld(&bar[XB_XGEN(b.x)]) == gen, bar);
.Lxb1_spin:
	global_load_dword v5, v202, s[74:75] offset:1024 sc1
	s_waitcnt vmcnt(0)
	v_sub_u32_e32 v5, v5, v4
	v_cmp_gt_i32_e32 vcc, 0, v5
	s_cbranch_vccz .Lxb1_done
	s_sleep 0
	s_add_i32 s18, s18, -1
	s_cmp_lg_u32 s18, 0
	s_cbranch_scc1 .Lxb1_spin

; __device__ __forceinline__ unsigned xb_ld(unsigned* p)              { return __hip_atomic_load(p, __ATOMIC_RELAXED, __HIP_MEMORY_SCOPE_AGENT); }
; #define XB_SPIN(cond, bar) do { unsigned _sp = 0; while (cond) { __builtin_amdgcn_s_sleep(1); \
;     if ((++_sp & 255u) == 0u) { if (xb_ld(&(bar)[XB_TMO])) break; if (_sp > XB_SPIN_CAP) { atomicAdd(&(bar)[XB_TMO], 1u); break; } } } } while (0)
; __device__ __forceinline__ void xcd_barrier(const XcdBarrier& b, const bool is_t0) {
;     ...
;             XB_SPIN(xb_ld(&bar[XB_XGEN(b.x)]) == gen, bar);
.Lxb2_spin:
	global_load_dword v5, v202, s[6:7] offset:1024 sc1
	s_waitcnt vmcnt(0)
	v_sub_u32_e32 v5, v5, v4
	v_cmp_gt_i32_e32 vcc, 0, v5
	s_cbranch_vccz .Lxb2_done
	s_sleep 0
	s_add_i32 s10, s10, -1
	s_cmp_lg_u32 s10, 0
	s_cbranch_scc1 .Lxb2_spin
